# v47
# speedup vs baseline: 1.0344x; 1.0008x over previous
; __device__ __forceinline__ void finishSM(f32x16& p0, f32x16& p1, float alpha, float& l_reg, bf16x8& pa0, bf16x8& pa1, bf16x8& pa2, bf16x8& pa3) {
;     for (int r = 0; r < 16; ++r) p1[r] = __builtin_amdgcn_exp2f(p1[r]);
;     float ps = 0; for (int r = 0; r < 16; ++r) ps += p0[r]; for (int r = 0; r < 16; ++r) ps += p1[r];
;     { auto rr = __builtin_amdgcn_permlane32_swap(__float_as_uint(ps), __float_as_uint(ps), false, false);
;       ps = __uint_as_float(rr[0]) + __uint_as_float(rr[1]); }
;     l_reg = l_reg * alpha + ps;
;     ...
;     PK4(p0, 0, pa0); PK4(p0, 8, pa1); PK4(p1, 0, pa2); PK4(p1, 8, pa3);
; template <int KB, bool SK>
; __device__ __forceinline__ void qkt(f32x16& p0, f32x16& p1, const char* K_lds, int r32, int hi, const bf16x8* qr, bool act) {
;     ...
;     for (int d0 = 0; d0 < 8; ++d0) { const char* a = kb[d0 & 3] + (d0 >> 2) * 128;
;         bf16x8 b0 = *reinterpret_cast<const bf16x8*>(a);
;         bf16x8 b1 = *reinterpret_cast<const bf16x8*>(a + 32 * 256);
;         p0 = __builtin_amdgcn_mfma_f32_32x32x16_bf16(b0, qr[d0], p0, 0, 0, 0);
;         p1 = __builtin_amdgcn_mfma_f32_32x32x16_bf16(b1, qr[d0], p1, 0, 0, 0); }
.LBB0_205:
	s_add_i32 s82, s74, 1
	s_lshl_b32 s82, s82, 8
	s_add_u32 s78, s100, s82
	s_addc_u32 s79, s101, 0
	s_add_u32 s80, s78, 0x2000
	s_addc_u32 s81, s79, 0
	v_lshl_add_u32 v240, v160, 8, v200
	global_load_dwordx4 v[128:131], v240, s[78:79]
	global_load_dwordx4 v[132:135], v240, s[80:81]
	ds_read_b128 v[64:67], v180 offset:49152
	ds_read_b128 v[68:71], v180 offset:57344
	ds_read_b128 v[224:227], v179 offset:49152
	ds_read_b128 v[248:251], v179 offset:57344
	ds_read_b128 v[216:219], v165 offset:49152
	ds_read_b128 v[220:223], v165 offset:57344
	v_exp_f32_e32 v240, v144
	v_add_f32_e32 v144, 0, v198
	v_add_f32_e32 v144, v199, v144
	v_add_f32_e32 v144, v210, v144
	v_add_f32_e32 v144, v212, v144
	v_add_f32_e32 v144, v213, v144
	s_waitcnt lgkmcnt(5)
	v_mfma_f32_32x32x16_bf16 v[80:95], v[64:67], v[124:127], 0
	v_add_f32_e32 v144, v215, v144
	v_add_f32_e32 v144, v211, v144
	v_add_f32_e32 v144, v214, v144
	v_add_f32_e32 v144, v190, v144
	s_waitcnt lgkmcnt(4)
	v_mfma_f32_32x32x16_bf16 v[64:79], v[68:71], v[124:127], 0
	v_add_f32_e32 v144, v192, v144
	v_add_f32_e32 v144, v193, v144
	v_add_f32_e32 v144, v196, v144
	v_add_f32_e32 v144, v191, v144
	v_add_f32_e32 v144, v194, v144
	v_add_f32_e32 v144, v195, v144
	s_waitcnt lgkmcnt(3)
	v_mfma_f32_32x32x16_bf16 v[80:95], v[224:227], v[120:123], v[80:95]
	v_add_f32_e32 v144, v197, v144
	v_exp_f32_e32 v241, v145
	v_exp_f32_e32 v242, v158
	v_exp_f32_e32 v243, v159
	s_waitcnt lgkmcnt(2)
	v_mfma_f32_32x32x16_bf16 v[64:79], v[248:251], v[120:123], v[64:79]
	ds_read_b128 v[224:227], v163 offset:49152
	ds_read_b128 v[248:251], v163 offset:57344
	v_exp_f32_e32 v244, v152
	v_exp_f32_e32 v245, v153
	v_exp_f32_e32 v246, v146
	v_exp_f32_e32 v247, v147
	v_cvt_pk_bf16_f32 v145, v210, v212
	v_cvt_pk_bf16_f32 v146, v213, v215
	s_waitcnt lgkmcnt(3)
	v_mfma_f32_32x32x16_bf16 v[80:95], v[216:219], v[116:119], v[80:95]
	v_cvt_pk_bf16_f32 v147, v211, v214
	v_cvt_pk_bf16_f32 v158, v244, v245
	v_cvt_pk_bf16_f32 v159, v246, v247
	s_sub_i32 s8, s74, 63
	s_waitcnt lgkmcnt(2)
	v_mfma_f32_32x32x16_bf16 v[64:79], v[220:223], v[116:119], v[64:79]
	ds_read_b128 v[216:219], v180 offset:49280
	ds_read_b128 v[220:223], v180 offset:57472
	v_permlane32_swap_b32_e32 v145, v147
	v_exp_f32_e32 v228, v156
	v_exp_f32_e32 v229, v157
	v_exp_f32_e32 v252, v154
	v_exp_f32_e32 v253, v155
	v_add_f32_e32 v144, v228, v144
	s_waitcnt lgkmcnt(3)
	v_mfma_f32_32x32x16_bf16 v[80:95], v[224:227], v[112:115], v[80:95]
	v_add_f32_e32 v144, v229, v144
	v_add_f32_e32 v144, v252, v144
	v_add_f32_e32 v144, v253, v144
	v_cvt_pk_bf16_f32 v152, v228, v229
	s_waitcnt lgkmcnt(2)
	v_mfma_f32_32x32x16_bf16 v[64:79], v[248:251], v[112:115], v[64:79]
	ds_read_b128 v[224:227], v179 offset:49280
	ds_read_b128 v[248:251], v179 offset:57472
	v_cvt_pk_bf16_f32 v153, v252, v253
	v_exp_f32_e32 v228, v150
	v_exp_f32_e32 v229, v151
	v_exp_f32_e32 v252, v148
	v_exp_f32_e32 v253, v149
	v_add_f32_e32 v144, v228, v144
	s_waitcnt lgkmcnt(3)
	v_mfma_f32_32x32x16_bf16 v[80:95], v[216:219], v[108:111], v[80:95]
	v_add_f32_e32 v144, v229, v144
	v_add_f32_e32 v144, v252, v144
	v_add_f32_e32 v144, v253, v144
	v_cvt_pk_bf16_f32 v154, v228, v229
	s_waitcnt lgkmcnt(2)
	v_mfma_f32_32x32x16_bf16 v[64:79], v[220:223], v[108:111], v[64:79]
	ds_read_b128 v[216:219], v165 offset:49280
	ds_read_b128 v[220:223], v165 offset:57472
	v_cvt_pk_bf16_f32 v155, v252, v253
	v_add_f32_e32 v144, v240, v144
	v_add_f32_e32 v144, v241, v144
	v_add_f32_e32 v144, v242, v144
	v_add_f32_e32 v144, v243, v144
	v_add_f32_e32 v144, v244, v144
	s_waitcnt lgkmcnt(3)
	v_mfma_f32_32x32x16_bf16 v[80:95], v[224:227], v[104:107], v[80:95]
	v_add_f32_e32 v144, v245, v144
	v_add_f32_e32 v144, v246, v144
	v_add_f32_e32 v186, v247, v144
	v_mov_b32_e32 v187, v186
	s_waitcnt lgkmcnt(2)
	v_mfma_f32_32x32x16_bf16 v[64:79], v[248:251], v[104:107], v[64:79]
	ds_read_b128 v[224:227], v163 offset:49280
	ds_read_b128 v[248:251], v163 offset:57472
	s_nop 1
	v_permlane32_swap_b32_e32 v186, v187
	v_cvt_pk_bf16_f32 v144, v198, v199
	v_cvt_pk_bf16_f32 v148, v190, v192
	v_cvt_pk_bf16_f32 v149, v193, v196
	v_cvt_pk_bf16_f32 v150, v191, v194
	s_waitcnt lgkmcnt(3)
	v_mfma_f32_32x32x16_bf16 v[80:95], v[216:219], v[100:103], v[80:95]
	v_cvt_pk_bf16_f32 v151, v195, v197
	v_cvt_pk_bf16_f32 v156, v240, v241
	v_cvt_pk_bf16_f32 v157, v242, v243
	v_permlane32_swap_b32_e32 v144, v146
	s_waitcnt lgkmcnt(2)
	v_mfma_f32_32x32x16_bf16 v[64:79], v[220:223], v[100:103], v[64:79]
	v_permlane32_swap_b32_e32 v148, v150
	v_permlane32_swap_b32_e32 v149, v151
	v_permlane32_swap_b32_e32 v152, v154
	v_permlane32_swap_b32_e32 v153, v155
	v_permlane32_swap_b32_e32 v156, v158
	v_permlane32_swap_b32_e32 v157, v159
	s_waitcnt lgkmcnt(1)
	v_mfma_f32_32x32x16_bf16 v[80:95], v[224:227], v[96:99], v[80:95]
	s_waitcnt lgkmcnt(0)
	v_mfma_f32_32x32x16_bf16 v[64:79], v[248:251], v[96:99], v[64:79]
	s_waitcnt vmcnt(2)
	ds_write_b128 v176, v[136:139] offset:32768
	ds_write_b128 v176, v[140:143] offset:40960
	s_add_i32 s82, s74, 0x41
	s_lshl_b32 s82, s82, 8
	s_add_u32 s78, s98, s82
	s_addc_u32 s79, s99, 0
	s_add_u32 s80, s78, 0x2000
	s_addc_u32 s81, s79, 0
	v_lshl_add_u32 v240, v160, 8, v200
	global_load_dwordx4 v[136:139], v240, s[78:79]
	global_load_dwordx4 v[140:143], v240, s[80:81]
	s_cmp_le_i32 s74, s70
	s_cselect_b64 s[42:43], -1, 0
	s_cmp_gt_i32 s8, s72
	s_cselect_b64 s[8:9], -1, 0
	s_and_b64 s[8:9], s[42:43], s[8:9]
	s_and_b64 vcc, exec, s[8:9]
	s_cbranch_vccnz .Lmy_h1_pv
; __device__ __forceinline__ void mask_tile(f32x16& p0, f32x16& p1, int dq, unsigned W) {
;     const float NEG = -__builtin_inff();
; #pragma unroll
;     for (int r = 0; r < 16; ++r) {
;         const int c = (r & 3) + 8 * (r >> 2);
;         if ((unsigned)(dq - c) >= W) p0[r] = NEG;
;         if ((unsigned)(dq - c - 32) >= W) p1[r] = NEG;
;     }
; }
; __device__ __forceinline__ void partialSM(f32x16& p0, f32x16& p1, float& m_reg, float& mn, float& alpha) {
;     float pmax = p0[0]; for (int r = 1; r < 16; ++r) pmax = fmaxf(pmax, p0[r]); for (int r = 0; r < 16; ++r) pmax = fmaxf(pmax, p1[r]);
;     { auto rr = __builtin_amdgcn_permlane32_swap(__float_as_uint(pmax), __float_as_uint(pmax), false, false);
;       pmax = fmaxf(__uint_as_float(rr[0]), __uint_as_float(rr[1])); }
	v_add_u32_e32 v239, 0x207b, v185
	v_cmp_gt_u32_e32 vcc, s62, v239
	v_add_u32_e32 v239, 0x5b, v185
	s_nop 0
	v_cndmask_b32_e32 v80, v235, v80, vcc
	v_cmp_lt_u32_e32 vcc, s65, v239
	v_add_u32_e32 v239, 0x7a, v185
	s_nop 0
	v_cndmask_b32_e32 v64, v235, v64, vcc
	v_cmp_lt_u32_e32 vcc, s65, v239
	v_add_u32_e32 v239, 0x5a, v185
	s_nop 0
	v_cndmask_b32_e32 v81, v235, v81, vcc
	v_cmp_lt_u32_e32 vcc, s65, v239
	v_add_u32_e32 v239, 0x79, v185
	s_nop 0
	v_cndmask_b32_e32 v65, v235, v65, vcc
	v_cmp_lt_u32_e32 vcc, s65, v239
	v_add_u32_e32 v239, 0x59, v185
	s_nop 0
	v_cndmask_b32_e32 v82, v235, v82, vcc
	v_cmp_lt_u32_e32 vcc, s65, v239
	v_add_u32_e32 v239, 0x78, v185
	s_nop 0
	v_cndmask_b32_e32 v66, v235, v66, vcc
	v_cmp_lt_u32_e32 vcc, s65, v239
	v_add_u32_e32 v239, 0x58, v185
	s_nop 0
	v_cndmask_b32_e32 v83, v235, v83, vcc
	v_cmp_lt_u32_e32 vcc, s65, v239
	v_add_u32_e32 v239, 0x73, v185
	s_nop 0
	v_cndmask_b32_e32 v67, v235, v67, vcc
	v_cmp_lt_u32_e32 vcc, s65, v239
	v_add_u32_e32 v239, 0x53, v185
	s_nop 0
	v_cndmask_b32_e32 v84, v235, v84, vcc
	v_cmp_lt_u32_e32 vcc, s65, v239
	v_add_u32_e32 v239, 0x72, v185
	s_nop 0
	v_cndmask_b32_e32 v68, v235, v68, vcc
	v_cmp_lt_u32_e32 vcc, s65, v239
	v_add_u32_e32 v239, 0x52, v185
	s_nop 0
	v_cndmask_b32_e32 v85, v235, v85, vcc
	v_cmp_lt_u32_e32 vcc, s65, v239
	v_add_u32_e32 v239, 0x71, v185
	s_nop 0
	v_cndmask_b32_e32 v69, v235, v69, vcc
	v_cmp_lt_u32_e32 vcc, s65, v239
	v_add_u32_e32 v239, 0x51, v185
	s_nop 0
	v_cndmask_b32_e32 v86, v235, v86, vcc
	v_cmp_lt_u32_e32 vcc, s65, v239
	v_add_u32_e32 v239, 0x70, v185
	s_nop 0
	v_cndmask_b32_e32 v70, v235, v70, vcc
	v_cmp_lt_u32_e32 vcc, s65, v239
	v_add_u32_e32 v239, 0x50, v185
	s_nop 0
	v_cndmask_b32_e32 v87, v235, v87, vcc
	v_cmp_lt_u32_e32 vcc, s65, v239
	v_add_u32_e32 v239, 0x6b, v185
	s_nop 0
	v_cndmask_b32_e32 v71, v235, v71, vcc
	v_cmp_lt_u32_e32 vcc, s65, v239
	v_add_u32_e32 v239, 0x4b, v185
	s_nop 0
	v_cndmask_b32_e32 v88, v235, v88, vcc
	v_cmp_lt_u32_e32 vcc, s65, v239
	v_add_u32_e32 v239, 0x6a, v185
	s_nop 0
	v_cndmask_b32_e32 v72, v235, v72, vcc
	v_cmp_lt_u32_e32 vcc, s65, v239
	v_add_u32_e32 v239, 0x4a, v185
	s_nop 0
	v_cndmask_b32_e32 v89, v235, v89, vcc
	v_cmp_lt_u32_e32 vcc, s65, v239
	v_add_u32_e32 v239, 0x69, v185
	s_nop 0
	v_cndmask_b32_e32 v73, v235, v73, vcc
	v_cmp_lt_u32_e32 vcc, s65, v239
	v_add_u32_e32 v239, 0x49, v185
	s_nop 0
	v_cndmask_b32_e32 v90, v235, v90, vcc
	v_cmp_lt_u32_e32 vcc, s65, v239
	v_add_u32_e32 v239, 0x68, v185
	s_nop 0
	v_cndmask_b32_e32 v74, v235, v74, vcc
	v_cmp_lt_u32_e32 vcc, s65, v239
	v_add_u32_e32 v239, 0x48, v185
	s_nop 0
	v_cndmask_b32_e32 v91, v235, v91, vcc
	v_cmp_lt_u32_e32 vcc, s65, v239
	v_add_u32_e32 v239, 0x63, v185
	s_nop 0
	v_cndmask_b32_e32 v75, v235, v75, vcc
	v_cmp_lt_u32_e32 vcc, s65, v239
	v_add_u32_e32 v239, 0x43, v185
	s_nop 0
	v_cndmask_b32_e32 v92, v235, v92, vcc
	v_cmp_lt_u32_e32 vcc, s65, v239
	v_add_u32_e32 v239, 0x62, v185
	s_nop 0
	v_cndmask_b32_e32 v76, v235, v76, vcc
	v_cmp_lt_u32_e32 vcc, s65, v239
	v_add_u32_e32 v239, 0x42, v185
	s_nop 0
	v_cndmask_b32_e32 v93, v235, v93, vcc
	v_cmp_lt_u32_e32 vcc, s65, v239
	v_add_u32_e32 v239, 0x61, v185
	s_nop 0
	v_cndmask_b32_e32 v77, v235, v77, vcc
	v_cmp_lt_u32_e32 vcc, s65, v239
	v_add_u32_e32 v239, 0x41, v185
	s_nop 0
	v_cndmask_b32_e32 v94, v235, v94, vcc
	v_cmp_lt_u32_e32 vcc, s65, v239
	v_add_u32_e32 v239, 0x60, v185
	s_nop 0
	v_cndmask_b32_e32 v78, v235, v78, vcc
	v_cmp_lt_u32_e32 vcc, s65, v239
	v_add_u32_e32 v239, 64, v185
	s_nop 0
	v_cndmask_b32_e32 v95, v235, v95, vcc
	v_cmp_lt_u32_e32 vcc, s65, v239
	s_nop 1
	v_cndmask_b32_e32 v79, v235, v79, vcc
.Lmy_h1_pv:
	ds_read_b64_tr_b16 v[224:225], v173 offset:0
	ds_read_b64_tr_b16 v[226:227], v173 offset:2048
	ds_read_b64_tr_b16 v[240:241], v173 offset:512
	ds_read_b64_tr_b16 v[242:243], v173 offset:2560
	ds_read_b64_tr_b16 v[244:245], v173 offset:1024
	ds_read_b64_tr_b16 v[246:247], v173 offset:3072
	ds_read_b64_tr_b16 v[248:249], v173 offset:1536
	ds_read_b64_tr_b16 v[250:251], v173 offset:3584
	v_max_f32_e32 v239, v81, v81
	v_max_f32_e32 v252, v80, v80
	v_max_f32_e32 v239, v252, v239
	s_waitcnt lgkmcnt(6)
	v_mfma_f32_32x32x16_bf16 v[32:47], v[144:147], v[224:227], v[32:47]
	v_max3_f32 v239, v239, v82, v83
	v_max3_f32 v239, v239, v84, v85
	ds_read_b64_tr_b16 v[224:225], v173 offset:4096
	ds_read_b64_tr_b16 v[226:227], v173 offset:6144
	v_max3_f32 v239, v239, v86, v87
	v_max3_f32 v239, v239, v88, v89
	v_max3_f32 v239, v239, v90, v91
	s_waitcnt lgkmcnt(6)
	v_mfma_f32_32x32x16_bf16 v[48:63], v[144:147], v[240:243], v[48:63]
	v_max3_f32 v239, v239, v92, v93
	v_max3_f32 v239, v239, v94, v95
	ds_read_b64_tr_b16 v[240:241], v173 offset:4608
	ds_read_b64_tr_b16 v[242:243], v173 offset:6656
	v_max3_f32 v239, v239, v64, v65
	v_max3_f32 v239, v239, v66, v67
	v_max3_f32 v239, v239, v68, v69
	s_waitcnt lgkmcnt(6)
	v_mfma_f32_32x32x16_bf16 v[16:31], v[144:147], v[244:247], v[16:31]
	v_max3_f32 v239, v239, v70, v71
	v_max3_f32 v239, v239, v72, v73
	ds_read_b64_tr_b16 v[244:245], v173 offset:5120
	ds_read_b64_tr_b16 v[246:247], v173 offset:7168
	v_max3_f32 v239, v239, v74, v75
	v_max3_f32 v239, v239, v76, v77
	v_max3_f32 v239, v239, v78, v79
	s_waitcnt lgkmcnt(6)
	v_mfma_f32_32x32x16_bf16 v[0:15], v[144:147], v[248:251], v[0:15]
	v_mov_b32_e32 v252, v239
	s_nop 1
	ds_read_b64_tr_b16 v[248:249], v173 offset:5632
	ds_read_b64_tr_b16 v[250:251], v173 offset:7680
	v_permlane32_swap_b32_e32 v239, v252
	v_max_f32_e32 v252, v252, v252
	v_max_f32_e32 v239, v239, v239
	s_waitcnt lgkmcnt(6)
; __device__ __forceinline__ void partialSM(f32x16& p0, f32x16& p1, float& m_reg, float& mn, float& alpha) {
;     float pmax = p0[0]; for (int r = 1; r < 16; ++r) pmax = fmaxf(pmax, p0[r]); for (int r = 0; r < 16; ++r) pmax = fmaxf(pmax, p1[r]);
;     { auto rr = __builtin_amdgcn_permlane32_swap(__float_as_uint(pmax), __float_as_uint(pmax), false, false);
;       pmax = fmaxf(__uint_as_float(rr[0]), __uint_as_float(rr[1])); }
;     constexpr float C2 = 1.4426950408889634f * SCALE;
;     if (__builtin_expect(__all((pmax - m_reg) * SCALE <= THR), 1)) { mn = m_reg; alpha = 1.f; }
;     else { mn = fmaxf(m_reg, pmax); alpha = __builtin_amdgcn_exp2f((m_reg - mn) * C2); m_reg = mn; }
;     const float mnL = -mn * C2;
;     for (int r = 0; r < 16; ++r) p0[r] = fmaf(p0[r], C2, mnL); for (int r = 0; r < 16; ++r) p1[r] = fmaf(p1[r], C2, mnL);
;     for (int r = 0; r < 16; ++r) p0[r] = __builtin_amdgcn_exp2f(p0[r]);
	v_mfma_f32_32x32x16_bf16 v[32:47], v[148:151], v[224:227], v[32:47]
	v_max_f32_e32 v239, v239, v252
	v_sub_f32_e32 v252, v239, v184
	ds_read_b64_tr_b16 v[224:225], v173 offset:8192
	ds_read_b64_tr_b16 v[226:227], v173 offset:10240
	v_mul_f32_e32 v252, 0x3db504f3, v252
	v_cmp_ge_f32_e32 vcc, s66, v252
	v_max_f32_e32 v252, v184, v184
	s_waitcnt lgkmcnt(6)
	v_mfma_f32_32x32x16_bf16 v[48:63], v[148:151], v[240:243], v[48:63]
	v_max_f32_e32 v239, v252, v239
	v_sub_f32_e32 v252, v184, v239
	ds_read_b64_tr_b16 v[240:241], v173 offset:8704
	ds_read_b64_tr_b16 v[242:243], v173 offset:10752
	v_mul_f32_e32 v252, 0x3e0293ee, v252
	v_exp_f32_e32 v252, v252
	s_cmp_eq_u64 vcc, exec
	s_waitcnt lgkmcnt(6)
	v_mfma_f32_32x32x16_bf16 v[16:31], v[148:151], v[244:247], v[16:31]
	s_cselect_b64 s[42:43], -1, 0
	v_cndmask_b32_e64 v184, v239, v184, s[42:43]
	ds_read_b64_tr_b16 v[244:245], v173 offset:9216
	ds_read_b64_tr_b16 v[246:247], v173 offset:11264
	v_mul_f32_e32 v228, 0xbe0293ee, v184
	v_fmamk_f32 v80, v80, 0x3e0293ee, v228
	v_fmamk_f32 v81, v81, 0x3e0293ee, v228
	s_waitcnt lgkmcnt(6)
	v_mfma_f32_32x32x16_bf16 v[0:15], v[148:151], v[248:251], v[0:15]
	v_fmamk_f32 v82, v82, 0x3e0293ee, v228
	v_fmamk_f32 v83, v83, 0x3e0293ee, v228
	ds_read_b64_tr_b16 v[248:249], v173 offset:9728
	ds_read_b64_tr_b16 v[250:251], v173 offset:11776
	v_fmamk_f32 v84, v84, 0x3e0293ee, v228
	v_fmamk_f32 v85, v85, 0x3e0293ee, v228
	v_fmamk_f32 v86, v86, 0x3e0293ee, v228
	s_waitcnt lgkmcnt(6)
	v_mfma_f32_32x32x16_bf16 v[32:47], v[152:155], v[224:227], v[32:47]
	v_fmamk_f32 v87, v87, 0x3e0293ee, v228
	v_fmamk_f32 v88, v88, 0x3e0293ee, v228
	ds_read_b64_tr_b16 v[224:225], v173 offset:12288
	ds_read_b64_tr_b16 v[226:227], v173 offset:14336
	v_fmamk_f32 v89, v89, 0x3e0293ee, v228
	v_fmamk_f32 v90, v90, 0x3e0293ee, v228
	v_fmamk_f32 v91, v91, 0x3e0293ee, v228
	s_waitcnt lgkmcnt(6)
	v_mfma_f32_32x32x16_bf16 v[48:63], v[152:155], v[240:243], v[48:63]
	v_fmamk_f32 v92, v92, 0x3e0293ee, v228
	v_fmamk_f32 v93, v93, 0x3e0293ee, v228
	ds_read_b64_tr_b16 v[240:241], v173 offset:12800
	ds_read_b64_tr_b16 v[242:243], v173 offset:14848
	v_fmamk_f32 v94, v94, 0x3e0293ee, v228
	v_fmamk_f32 v95, v95, 0x3e0293ee, v228
	v_exp_f32_e32 v144, v80
	s_waitcnt lgkmcnt(6)
	v_mfma_f32_32x32x16_bf16 v[16:31], v[152:155], v[244:247], v[16:31]
	v_exp_f32_e32 v145, v81
	v_exp_f32_e32 v146, v82
	ds_read_b64_tr_b16 v[244:245], v173 offset:13312
	ds_read_b64_tr_b16 v[246:247], v173 offset:15360
	v_exp_f32_e32 v147, v86
	v_fmamk_f32 v199, v64, 0x3e0293ee, v228
	v_fmamk_f32 v210, v65, 0x3e0293ee, v228
	s_waitcnt lgkmcnt(6)
	v_mfma_f32_32x32x16_bf16 v[0:15], v[152:155], v[248:251], v[0:15]
	v_fmamk_f32 v211, v66, 0x3e0293ee, v228
	v_fmamk_f32 v212, v67, 0x3e0293ee, v228
	ds_read_b64_tr_b16 v[248:249], v173 offset:13824
	ds_read_b64_tr_b16 v[250:251], v173 offset:15872
	v_exp_f32_e32 v148, v88
	v_exp_f32_e32 v149, v89
	v_exp_f32_e32 v150, v92
	s_waitcnt lgkmcnt(6)
	v_mfma_f32_32x32x16_bf16 v[32:47], v[156:159], v[224:227], v[32:47]
	v_exp_f32_e32 v151, v93
	v_fmamk_f32 v213, v68, 0x3e0293ee, v228
	v_fmamk_f32 v192, v69, 0x3e0293ee, v228
	v_fmamk_f32 v193, v70, 0x3e0293ee, v228
	v_fmamk_f32 v194, v71, 0x3e0293ee, v228
	s_waitcnt lgkmcnt(4)
	v_mfma_f32_32x32x16_bf16 v[48:63], v[156:159], v[240:243], v[48:63]
	v_fmamk_f32 v195, v72, 0x3e0293ee, v228
	v_fmamk_f32 v196, v73, 0x3e0293ee, v228
	v_exp_f32_e32 v152, v94
	v_exp_f32_e32 v153, v95
	v_exp_f32_e32 v154, v90
	s_waitcnt lgkmcnt(2)
	v_mfma_f32_32x32x16_bf16 v[16:31], v[156:159], v[244:247], v[16:31]
	v_exp_f32_e32 v155, v91
	v_fmamk_f32 v197, v74, 0x3e0293ee, v228
	v_fmamk_f32 v198, v75, 0x3e0293ee, v228
	v_fmamk_f32 v191, v76, 0x3e0293ee, v228
	v_fmamk_f32 v214, v77, 0x3e0293ee, v228
	s_waitcnt lgkmcnt(0)
	v_mfma_f32_32x32x16_bf16 v[0:15], v[156:159], v[248:251], v[0:15]
	v_fmamk_f32 v215, v78, 0x3e0293ee, v228
	v_fmamk_f32 v190, v79, 0x3e0293ee, v228
	v_exp_f32_e32 v156, v87
	v_exp_f32_e32 v157, v83
	v_exp_f32_e32 v158, v84
	v_exp_f32_e32 v159, v85
	s_waitcnt lgkmcnt(0)
	s_barrier
	v_cndmask_b32_e64 v189, v252, 1.0, s[42:43]
	v_cmp_gt_f32_e32 vcc, 1.0, v189
	s_waitcnt vmcnt(2)
	ds_write_b128 v181, v[128:131]
	ds_write_b128 v182, v[132:135]
	s_cbranch_vccz .LBB0_211
	s_and_saveexec_b64 s[8:9], s[40:41]
	ds_write_b32 v175, v189 offset:128
	s_or_b64 exec, exec, s[8:9]
	s_waitcnt lgkmcnt(0)
	ds_read_b128 v[128:131], v174 offset:224
	ds_read_b128 v[132:135], v174 offset:192
	ds_read_b128 v[80:83], v174 offset:160
	ds_read_b128 v[84:87], v174 offset:128
	s_waitcnt lgkmcnt(3)
	v_pk_mul_f32 v[46:47], v[46:47], v[130:131]
	s_waitcnt lgkmcnt(2)
	v_pk_mul_f32 v[42:43], v[42:43], v[134:135]
	s_waitcnt lgkmcnt(1)
	v_pk_mul_f32 v[38:39], v[38:39], v[82:83]
	s_waitcnt lgkmcnt(0)
	v_pk_mul_f32 v[34:35], v[34:35], v[86:87]
	v_pk_mul_f32 v[44:45], v[44:45], v[128:129]
	v_pk_mul_f32 v[40:41], v[40:41], v[132:133]
	v_pk_mul_f32 v[36:37], v[36:37], v[80:81]
	v_pk_mul_f32 v[32:33], v[32:33], v[84:85]
	v_pk_mul_f32 v[62:63], v[62:63], v[130:131]
	v_pk_mul_f32 v[58:59], v[58:59], v[134:135]
	v_pk_mul_f32 v[54:55], v[54:55], v[82:83]
	v_pk_mul_f32 v[50:51], v[50:51], v[86:87]
	v_pk_mul_f32 v[60:61], v[60:61], v[128:129]
	v_pk_mul_f32 v[56:57], v[56:57], v[132:133]
	v_pk_mul_f32 v[52:53], v[52:53], v[80:81]
	v_pk_mul_f32 v[48:49], v[48:49], v[84:85]
	v_pk_mul_f32 v[30:31], v[30:31], v[130:131]
	v_pk_mul_f32 v[26:27], v[26:27], v[134:135]
	v_pk_mul_f32 v[22:23], v[22:23], v[82:83]
	v_pk_mul_f32 v[18:19], v[18:19], v[86:87]
	v_pk_mul_f32 v[28:29], v[28:29], v[128:129]
	v_pk_mul_f32 v[24:25], v[24:25], v[132:133]
	v_pk_mul_f32 v[20:21], v[20:21], v[80:81]
	v_pk_mul_f32 v[16:17], v[16:17], v[84:85]
	v_pk_mul_f32 v[14:15], v[14:15], v[130:131]
	v_pk_mul_f32 v[10:11], v[10:11], v[134:135]
	v_pk_mul_f32 v[6:7], v[6:7], v[82:83]
	v_pk_mul_f32 v[2:3], v[2:3], v[86:87]
	v_pk_mul_f32 v[12:13], v[12:13], v[128:129]
	v_pk_mul_f32 v[8:9], v[8:9], v[132:133]
	v_pk_mul_f32 v[4:5], v[4:5], v[80:81]
	v_pk_mul_f32 v[0:1], v[0:1], v[84:85]

; __device__ __forceinline__ void mask_tile(f32x16& p0, f32x16& p1, int dq, unsigned W) {
;     const float NEG = -__builtin_inff();
; #pragma unroll
;     for (int r = 0; r < 16; ++r) {
;         const int c = (r & 3) + 8 * (r >> 2);
;         if ((unsigned)(dq - c) >= W) p0[r] = NEG;
;         if ((unsigned)(dq - c - 32) >= W) p1[r] = NEG;
;     }
; }
.LBB0_213:
	s_waitcnt vmcnt(2)
	s_andn2_b64 vcc, exec, s[8:9]
	s_cbranch_vccnz .Lmy_h2_skipk
	ds_write_b128 v176, v[136:139] offset:49152
	ds_write_b128 v176, v[140:143] offset:57344
.Lmy_h2_skipk:
	s_add_i32 s82, s74, 0x81
	s_lshl_b32 s82, s82, 8
	s_add_u32 s78, s98, s82
	s_addc_u32 s79, s99, 0
	s_add_u32 s80, s78, 0x2000
	s_addc_u32 s81, s79, 0
	v_lshl_add_u32 v240, v160, 8, v200
	global_load_dwordx4 v[136:139], v240, s[78:79]
	global_load_dwordx4 v[140:143], v240, s[80:81]
	s_add_i32 s42, s74, 64
	s_add_i32 s75, s74, 1
	s_cmp_le_i32 s42, s70
	s_cselect_b64 s[42:43], -1, 0
	s_cmp_gt_i32 s75, s72
	s_cselect_b64 s[76:77], -1, 0
	s_and_b64 s[42:43], s[42:43], s[76:77]
	s_and_b64 vcc, exec, s[42:43]
	s_cbranch_vccnz .Lmy_h2_pv
	v_add_u32_e32 v239, 0x203b, v185
	v_cmp_gt_u32_e32 vcc, s62, v239
	v_add_u32_e32 v239, 27, v185
	s_nop 0
	v_cndmask_b32_e32 v80, v235, v80, vcc
	v_cmp_lt_u32_e32 vcc, s65, v239
	v_add_u32_e32 v239, 58, v185
	s_nop 0
	v_cndmask_b32_e32 v64, v235, v64, vcc
	v_cmp_lt_u32_e32 vcc, s65, v239
	v_add_u32_e32 v239, 26, v185
	s_nop 0
	v_cndmask_b32_e32 v81, v235, v81, vcc
	v_cmp_lt_u32_e32 vcc, s65, v239
	v_add_u32_e32 v239, 57, v185
	s_nop 0
	v_cndmask_b32_e32 v65, v235, v65, vcc
	v_cmp_lt_u32_e32 vcc, s65, v239
	v_add_u32_e32 v239, 25, v185
	s_nop 0
	v_cndmask_b32_e32 v82, v235, v82, vcc
	v_cmp_lt_u32_e32 vcc, s65, v239
	v_add_u32_e32 v239, 56, v185
	s_nop 0
	v_cndmask_b32_e32 v66, v235, v66, vcc
	v_cmp_lt_u32_e32 vcc, s65, v239
	v_add_u32_e32 v239, 24, v185
	s_nop 0
	v_cndmask_b32_e32 v83, v235, v83, vcc
	v_cmp_lt_u32_e32 vcc, s65, v239
	v_add_u32_e32 v239, 51, v185
	s_nop 0
	v_cndmask_b32_e32 v67, v235, v67, vcc
	v_cmp_lt_u32_e32 vcc, s65, v239
	v_add_u32_e32 v239, 19, v185
	s_nop 0
	v_cndmask_b32_e32 v84, v235, v84, vcc
	v_cmp_lt_u32_e32 vcc, s65, v239
	v_add_u32_e32 v239, 50, v185
	s_nop 0
	v_cndmask_b32_e32 v68, v235, v68, vcc
	v_cmp_lt_u32_e32 vcc, s65, v239
	v_add_u32_e32 v239, 18, v185
	s_nop 0
	v_cndmask_b32_e32 v85, v235, v85, vcc
	v_cmp_lt_u32_e32 vcc, s65, v239
	v_add_u32_e32 v239, 49, v185
	s_nop 0
	v_cndmask_b32_e32 v69, v235, v69, vcc
	v_cmp_lt_u32_e32 vcc, s65, v239
	v_add_u32_e32 v239, 17, v185
	s_nop 0
	v_cndmask_b32_e32 v86, v235, v86, vcc
	v_cmp_lt_u32_e32 vcc, s65, v239
	v_add_u32_e32 v239, 48, v185
	s_nop 0
	v_cndmask_b32_e32 v70, v235, v70, vcc
	v_cmp_lt_u32_e32 vcc, s65, v239
	v_add_u32_e32 v239, 16, v185
	s_nop 0
	v_cndmask_b32_e32 v87, v235, v87, vcc
	v_cmp_lt_u32_e32 vcc, s65, v239
	v_add_u32_e32 v239, 43, v185
	s_nop 0
	v_cndmask_b32_e32 v71, v235, v71, vcc
	v_cmp_lt_u32_e32 vcc, s65, v239
	v_add_u32_e32 v239, 11, v185
	s_nop 0
	v_cndmask_b32_e32 v88, v235, v88, vcc
	v_cmp_lt_u32_e32 vcc, s65, v239
	v_add_u32_e32 v239, 42, v185
	s_nop 0
	v_cndmask_b32_e32 v72, v235, v72, vcc
	v_cmp_lt_u32_e32 vcc, s65, v239
	v_add_u32_e32 v239, 10, v185
	s_nop 0
	v_cndmask_b32_e32 v89, v235, v89, vcc
	v_cmp_lt_u32_e32 vcc, s65, v239
	v_add_u32_e32 v239, 41, v185
	s_nop 0
	v_cndmask_b32_e32 v73, v235, v73, vcc
	v_cmp_lt_u32_e32 vcc, s65, v239
	v_add_u32_e32 v239, 9, v185
	s_nop 0
	v_cndmask_b32_e32 v90, v235, v90, vcc
	v_cmp_lt_u32_e32 vcc, s65, v239
	v_add_u32_e32 v239, 40, v185
	s_nop 0
	v_cndmask_b32_e32 v74, v235, v74, vcc
	v_cmp_lt_u32_e32 vcc, s65, v239
	v_add_u32_e32 v239, 8, v185
	s_nop 0
	v_cndmask_b32_e32 v91, v235, v91, vcc
	v_cmp_lt_u32_e32 vcc, s65, v239
	v_add_u32_e32 v239, 35, v185
	s_nop 0
	v_cndmask_b32_e32 v75, v235, v75, vcc
	v_cmp_lt_u32_e32 vcc, s65, v239
	v_add_u32_e32 v239, 3, v185
	s_nop 0
	v_cndmask_b32_e32 v92, v235, v92, vcc
	v_cmp_lt_u32_e32 vcc, s65, v239
	v_add_u32_e32 v239, 34, v185
	s_nop 0
	v_cndmask_b32_e32 v76, v235, v76, vcc
	v_cmp_lt_u32_e32 vcc, s65, v239
	v_add_u32_e32 v239, 2, v185
	s_nop 0
	v_cndmask_b32_e32 v93, v235, v93, vcc
	v_cmp_lt_u32_e32 vcc, s65, v239
	v_add_u32_e32 v239, 33, v185
	s_nop 0
	v_cndmask_b32_e32 v77, v235, v77, vcc
	v_cmp_lt_u32_e32 vcc, s65, v239
	v_add_u32_e32 v239, 1, v185
	s_nop 0
	v_cndmask_b32_e32 v94, v235, v94, vcc
	v_cmp_lt_u32_e32 vcc, s65, v239
	v_add_u32_e32 v239, 32, v185
	s_nop 0
	v_cndmask_b32_e32 v78, v235, v78, vcc
	v_cmp_lt_u32_e32 vcc, s65, v239
	s_nop 1
	v_cndmask_b32_e32 v95, v235, v95, vcc
	v_cmp_lt_u32_e32 vcc, s65, v185
	s_nop 1
	v_cndmask_b32_e32 v79, v235, v79, vcc
; __device__ __forceinline__ void partialSM(f32x16& p0, f32x16& p1, float& m_reg, float& mn, float& alpha) {
;     float pmax = p0[0]; for (int r = 1; r < 16; ++r) pmax = fmaxf(pmax, p0[r]); for (int r = 0; r < 16; ++r) pmax = fmaxf(pmax, p1[r]);
;     { auto rr = __builtin_amdgcn_permlane32_swap(__float_as_uint(pmax), __float_as_uint(pmax), false, false);
;       pmax = fmaxf(__uint_as_float(rr[0]), __uint_as_float(rr[1])); }
;     constexpr float C2 = 1.4426950408889634f * SCALE;
;     if (__builtin_expect(__all((pmax - m_reg) * SCALE <= THR), 1)) { mn = m_reg; alpha = 1.f; }
;     else { mn = fmaxf(m_reg, pmax); alpha = __builtin_amdgcn_exp2f((m_reg - mn) * C2); m_reg = mn; }
;     const float mnL = -mn * C2;
;     for (int r = 0; r < 16; ++r) p0[r] = fmaf(p0[r], C2, mnL); for (int r = 0; r < 16; ++r) p1[r] = fmaf(p1[r], C2, mnL);
;     for (int r = 0; r < 16; ++r) p0[r] = __builtin_amdgcn_exp2f(p0[r]);
.Lmy_h2_pv:
	ds_read_b64_tr_b16 v[224:225], v173 offset:16384
	ds_read_b64_tr_b16 v[226:227], v173 offset:18432
	ds_read_b64_tr_b16 v[240:241], v173 offset:16896
	ds_read_b64_tr_b16 v[242:243], v173 offset:18944
	ds_read_b64_tr_b16 v[244:245], v173 offset:17408
	ds_read_b64_tr_b16 v[246:247], v173 offset:19456
	ds_read_b64_tr_b16 v[248:249], v173 offset:17920
	ds_read_b64_tr_b16 v[250:251], v173 offset:19968
	v_max_f32_e32 v239, v81, v81
	v_max_f32_e32 v252, v80, v80
	v_max_f32_e32 v239, v252, v239
	s_waitcnt lgkmcnt(6)
	v_mfma_f32_32x32x16_bf16 v[32:47], v[144:147], v[224:227], v[32:47]
	v_max3_f32 v239, v239, v82, v83
	v_max3_f32 v239, v239, v84, v85
	ds_read_b64_tr_b16 v[224:225], v173 offset:20480
	ds_read_b64_tr_b16 v[226:227], v173 offset:22528
	v_max3_f32 v239, v239, v86, v87
	v_max3_f32 v239, v239, v88, v89
	v_max3_f32 v239, v239, v90, v91
	s_waitcnt lgkmcnt(6)
	v_mfma_f32_32x32x16_bf16 v[48:63], v[144:147], v[240:243], v[48:63]
	v_max3_f32 v239, v239, v92, v93
	v_max3_f32 v239, v239, v94, v95
	ds_read_b64_tr_b16 v[240:241], v173 offset:20992
	ds_read_b64_tr_b16 v[242:243], v173 offset:23040
	v_max3_f32 v239, v239, v64, v65
	v_max3_f32 v239, v239, v66, v67
	v_max3_f32 v239, v239, v68, v69
	s_waitcnt lgkmcnt(6)
	v_mfma_f32_32x32x16_bf16 v[16:31], v[144:147], v[244:247], v[16:31]
	v_max3_f32 v239, v239, v70, v71
	v_max3_f32 v239, v239, v72, v73
	ds_read_b64_tr_b16 v[244:245], v173 offset:21504
	ds_read_b64_tr_b16 v[246:247], v173 offset:23552
	v_max3_f32 v239, v239, v74, v75
	v_max3_f32 v239, v239, v76, v77
	v_max3_f32 v239, v239, v78, v79
	s_waitcnt lgkmcnt(6)
	v_mfma_f32_32x32x16_bf16 v[0:15], v[144:147], v[248:251], v[0:15]
	v_mov_b32_e32 v252, v239
	s_nop 1
	ds_read_b64_tr_b16 v[248:249], v173 offset:22016
	ds_read_b64_tr_b16 v[250:251], v173 offset:24064
	v_permlane32_swap_b32_e32 v239, v252
	v_max_f32_e32 v252, v252, v252
	v_max_f32_e32 v239, v239, v239
	s_waitcnt lgkmcnt(6)
	v_mfma_f32_32x32x16_bf16 v[32:47], v[148:151], v[224:227], v[32:47]
	v_max_f32_e32 v239, v239, v252
	v_sub_f32_e32 v252, v239, v184
	ds_read_b64_tr_b16 v[224:225], v173 offset:24576
	ds_read_b64_tr_b16 v[226:227], v173 offset:26624
	v_mul_f32_e32 v252, 0x3db504f3, v252
	v_cmp_ge_f32_e32 vcc, s66, v252
	s_cmp_eq_u64 vcc, exec
	s_waitcnt lgkmcnt(6)
	v_mfma_f32_32x32x16_bf16 v[48:63], v[148:151], v[240:243], v[48:63]
	s_cselect_b64 s[42:43], -1, 0
	v_max_f32_e32 v253, v184, v184
	ds_read_b64_tr_b16 v[240:241], v173 offset:25088
	ds_read_b64_tr_b16 v[242:243], v173 offset:27136
	v_max_f32_e32 v253, v253, v239
	v_sub_f32_e32 v252, v184, v253
	v_mul_f32_e32 v252, 0x3e0293ee, v252
	s_waitcnt lgkmcnt(6)
	v_mfma_f32_32x32x16_bf16 v[16:31], v[148:151], v[244:247], v[16:31]
	v_exp_f32_e32 v252, v252
	s_nop 0
	ds_read_b64_tr_b16 v[244:245], v173 offset:25600
	ds_read_b64_tr_b16 v[246:247], v173 offset:27648
	v_cndmask_b32_e64 v188, v252, 1.0, s[42:43]
	v_cndmask_b32_e64 v184, v253, v184, s[42:43]
	v_mul_f32_e32 v228, 0xbe0293ee, v184
	s_waitcnt lgkmcnt(6)
	v_mfma_f32_32x32x16_bf16 v[0:15], v[148:151], v[248:251], v[0:15]
	v_mov_b32_e32 v229, v228
	v_fmamk_f32 v80, v80, 0x3e0293ee, v228
	ds_read_b64_tr_b16 v[248:249], v173 offset:26112
	ds_read_b64_tr_b16 v[250:251], v173 offset:28160
	v_fmamk_f32 v81, v81, 0x3e0293ee, v228
	v_fmamk_f32 v82, v82, 0x3e0293ee, v228
	v_fmamk_f32 v83, v83, 0x3e0293ee, v228
	s_waitcnt lgkmcnt(6)
	v_mfma_f32_32x32x16_bf16 v[32:47], v[152:155], v[224:227], v[32:47]
	v_fmamk_f32 v84, v84, 0x3e0293ee, v228
	v_fmamk_f32 v85, v85, 0x3e0293ee, v228
	ds_read_b64_tr_b16 v[224:225], v173 offset:28672
	ds_read_b64_tr_b16 v[226:227], v173 offset:30720
	v_fmamk_f32 v86, v86, 0x3e0293ee, v228
	v_fmamk_f32 v87, v87, 0x3e0293ee, v228
	v_fmamk_f32 v88, v88, 0x3e0293ee, v228
	s_waitcnt lgkmcnt(6)
	v_mfma_f32_32x32x16_bf16 v[48:63], v[152:155], v[240:243], v[48:63]
	v_fmamk_f32 v89, v89, 0x3e0293ee, v228
	v_fmamk_f32 v90, v90, 0x3e0293ee, v228
	ds_read_b64_tr_b16 v[240:241], v173 offset:29184
	ds_read_b64_tr_b16 v[242:243], v173 offset:31232
	v_fmamk_f32 v91, v91, 0x3e0293ee, v228
	v_fmamk_f32 v92, v92, 0x3e0293ee, v228
	v_fmamk_f32 v93, v93, 0x3e0293ee, v228
	s_waitcnt lgkmcnt(6)
	v_mfma_f32_32x32x16_bf16 v[16:31], v[152:155], v[244:247], v[16:31]
	v_fmamk_f32 v94, v94, 0x3e0293ee, v228
	v_fmac_f32_e32 v229, 0x3e0293ee, v95
	ds_read_b64_tr_b16 v[244:245], v173 offset:29696
	ds_read_b64_tr_b16 v[246:247], v173 offset:31744
	v_exp_f32_e32 v198, v80
	v_exp_f32_e32 v199, v81
	v_exp_f32_e32 v210, v82
	s_waitcnt lgkmcnt(6)
	v_mfma_f32_32x32x16_bf16 v[0:15], v[152:155], v[248:251], v[0:15]
	v_exp_f32_e32 v212, v83
	v_exp_f32_e32 v213, v84
	ds_read_b64_tr_b16 v[248:249], v173 offset:30208
	ds_read_b64_tr_b16 v[250:251], v173 offset:32256
	v_exp_f32_e32 v215, v85
	v_exp_f32_e32 v211, v86
	v_exp_f32_e32 v214, v87
	s_waitcnt lgkmcnt(6)
	v_mfma_f32_32x32x16_bf16 v[32:47], v[156:159], v[224:227], v[32:47]
	v_exp_f32_e32 v190, v88
	v_exp_f32_e32 v192, v89
	v_exp_f32_e32 v193, v90
	v_exp_f32_e32 v196, v91
	v_exp_f32_e32 v191, v92
	s_waitcnt lgkmcnt(4)
	v_mfma_f32_32x32x16_bf16 v[48:63], v[156:159], v[240:243], v[48:63]
	v_exp_f32_e32 v194, v93
	v_exp_f32_e32 v195, v94
	v_exp_f32_e32 v197, v229
	v_fmamk_f32 v144, v72, 0x3e0293ee, v228
	v_fmamk_f32 v145, v73, 0x3e0293ee, v228
	s_waitcnt lgkmcnt(2)
	v_mfma_f32_32x32x16_bf16 v[16:31], v[156:159], v[244:247], v[16:31]
	v_fmamk_f32 v146, v78, 0x3e0293ee, v228
	v_fmamk_f32 v147, v79, 0x3e0293ee, v228
	v_fmamk_f32 v148, v70, 0x3e0293ee, v228
	v_fmamk_f32 v149, v71, 0x3e0293ee, v228
	v_fmamk_f32 v150, v68, 0x3e0293ee, v228
	s_waitcnt lgkmcnt(0)
	v_mfma_f32_32x32x16_bf16 v[0:15], v[156:159], v[248:251], v[0:15]
	v_fmamk_f32 v151, v69, 0x3e0293ee, v228
	v_fmamk_f32 v152, v76, 0x3e0293ee, v228
	v_fmamk_f32 v153, v77, 0x3e0293ee, v228
	v_fmamk_f32 v154, v66, 0x3e0293ee, v228
	v_fmamk_f32 v155, v67, 0x3e0293ee, v228
	v_fmamk_f32 v156, v64, 0x3e0293ee, v228
	v_fmamk_f32 v157, v65, 0x3e0293ee, v228
	v_fmamk_f32 v158, v74, 0x3e0293ee, v228
	v_fmamk_f32 v159, v75, 0x3e0293ee, v228
	s_waitcnt lgkmcnt(0)
	s_barrier
	s_waitcnt vmcnt(2)
	s_andn2_b64 vcc, exec, s[8:9]
	s_cbranch_vccnz .LBB0_217
	ds_write_b128 v181, v[128:131] offset:16384
	ds_write_b128 v182, v[132:135] offset:16384
